# hand-written q/k (rope) epilogue of the mixer in-projection: rope rows ring-prefetched, shuffles pipelined, branch-free; rope L1 prefetch dropped
# baseline (speedup 1.0000x reference)
; __device__ __forceinline__ unsigned cvt_pk_bf16(float lo, float hi) { const f32x2c v = {lo, hi}; const bf16x2c b = __builtin_convertvector(v, bf16x2c); return __builtin_bit_cast(unsigned, b); }
; #define PG8_GAS __attribute__((address_space(1)))
;     __device__ __forceinline__ void operator()(const f32x4 (&acc)[2][2][4][2], const Unit& u, int wr, int wc, int fr, int fq) const {
;         const int seg = u.pn >> 1; const int rbase = u.pm * BM + wr * 64 + fr; const int b = u.pm >> 5;
;         bf16_t* segp = proj + (size_t)seg * ((size_t)65536 * 512);
; #pragma unroll
;         for (int bj = 0; bj < 2; ++bj) {
;             const int wcol = (u.pn & 1) * 256 + bj * HALF + wc * 32 + 8 * fq;
;             if (seg < 3) {
;                 const int head = wcol >> 6, ch = wcol & 63;
;                 const bool rotw = (seg < 2) && ((wc & 1) == 0);
; #pragma unroll
;                 for (int ai = 0; ai < 2; ++ai)
; #pragma unroll
;                     for (int m = 0; m < 4; ++m) {
;                         const int r = rbase + ai * HALF + m * 16; const int s = r & 8191;
;                         f32x4 v0 = acc[ai][bj][m][0], v1 = acc[ai][bj][m][1];
;                         if (rotw) {
;                             f32x4 p0, p1;
; #pragma unroll
;                             for (int j = 0; j < 4; ++j) { p0[j] = __shfl_xor(v0[j], 16); p1[j] = __shfl_xor(v1[j], 16); }
;                             if (fq < 2) {
;                                 const f32x4 c0 = *(const PG8_GAS f32x4*)(rope + (size_t)r * 16), c1 = *(const PG8_GAS f32x4*)(rope + (size_t)r * 16 + 4);
;                                 const f32x4 s0 = *(const PG8_GAS f32x4*)(rope + (size_t)r * 16 + 8), s1 = *(const PG8_GAS f32x4*)(rope + (size_t)r * 16 + 12);
;                                 if (fq == 0) { v0 = v0 * c0 - p0 * s0; v1 = v1 * c1 - p1 * s1; }
;                                 else { v0 = v0 * c0 + p0 * s0; v1 = v1 * c1 + p1 * s1; }
;                             }
;                         }
;                         if (seg == 0) { v0 = v0 * 0.18033688011112042f; v1 = v1 * 0.18033688011112042f; }
;                         u32x4 w; w.x = cvt_pk_bf16(v0[0], v0[1]); w.y = cvt_pk_bf16(v0[2], v0[3]); w.z = cvt_pk_bf16(v1[0], v1[1]); w.w = cvt_pk_bf16(v1[2], v1[3]);
;                         *(PG8_GAS u32x4*)(segp + ((size_t)((b * 8 + head) * 8192 + s)) * 64 + ch) = w;
.LBB0_153:
	s_cmp_lt_u32 s0, 4
	s_cbranch_scc0 .Lrope_old
	s_cmp_lt_u32 s0, 2
	s_cselect_b32 s28, s78, 1.0
	s_mov_b32 s29, 0
	s_lshr_b32 s30, s0, 1
	s_lshl_b32 s31, s30, 26
	s_add_u32 s26, s92, s31
	s_addc_u32 s27, s93, 0
	v_readlane_b32 s30, v255, 12
	s_and_b32 s31, s0, 1
	s_lshl_b32 s31, s31, 2
	s_lshr_b32 s32, s30, 6
	s_add_i32 s31, s31, s32
	s_lshr_b32 s32, s54, 5
	s_lshl_b32 s32, s32, 3
	s_add_i32 s31, s31, s32
	s_lshl_b32 s31, s31, 20
	s_and_b32 s32, s54, 31
	s_lshl_b32 s32, s32, 15
	s_add_u32 s31, s31, s32
	s_add_u32 s26, s26, s31
	s_addc_u32 s27, s27, 0
	s_add_u32 s98, s26, 0x200000
	s_addc_u32 s99, s27, 0
	s_and_b32 s32, s30, 32
	s_lshl_b32 s32, s32, 1
	v_lshlrev_b32_e32 v169, 7, v160
	v_lshl_add_u32 v169, v161, 1, v169
	v_add_u32_e32 v169, s32, v169
	v_readlane_b32 s30, v255, 15
	s_nop 3
	s_cmp_lg_u32 s30, 0
	s_cbranch_scc0 .Lrope_plain
	s_lshl_b32 s30, s54, 14
	s_add_u32 s24, s48, s30
	s_addc_u32 s25, s49, 0
	v_lshlrev_b32_e32 v168, 6, v160
	v_lshlrev_b32_e32 v202, 2, v207
	v_cmp_eq_u32_e32 vcc, 0, v161
	v_bfrev_b32_e32 v244, 1
	s_nop 0
	v_cndmask_b32_e32 v252, 0, v244, vcc
	global_load_dwordx4 v[128:131], v168, s[24:25] offset:0
	global_load_dwordx4 v[132:135], v168, s[24:25] offset:16
	global_load_dwordx4 v[136:139], v168, s[24:25] offset:32
	global_load_dwordx4 v[140:143], v168, s[24:25] offset:48
	global_load_dwordx4 v[180:183], v168, s[24:25] offset:1024
	global_load_dwordx4 v[184:187], v168, s[24:25] offset:1040
	global_load_dwordx4 v[188:191], v168, s[24:25] offset:1056
	global_load_dwordx4 v[192:195], v168, s[24:25] offset:1072
	global_load_dwordx4 v[214:217], v168, s[24:25] offset:2048
	global_load_dwordx4 v[218:221], v168, s[24:25] offset:2064
	global_load_dwordx4 v[222:225], v168, s[24:25] offset:2080
	global_load_dwordx4 v[226:229], v168, s[24:25] offset:2096
	ds_bpermute_b32 v230, v202, v120
	ds_bpermute_b32 v231, v202, v121
	ds_bpermute_b32 v232, v202, v122
	ds_bpermute_b32 v233, v202, v123
	ds_bpermute_b32 v234, v202, v124
	ds_bpermute_b32 v235, v202, v125
	ds_bpermute_b32 v236, v202, v126
	ds_bpermute_b32 v237, v202, v127
	ds_bpermute_b32 v196, v202, v56
	ds_bpermute_b32 v197, v202, v57
	ds_bpermute_b32 v198, v202, v58
	ds_bpermute_b32 v199, v202, v59
	ds_bpermute_b32 v156, v202, v60
	ds_bpermute_b32 v157, v202, v61
	ds_bpermute_b32 v158, v202, v62
	ds_bpermute_b32 v159, v202, v63
	s_waitcnt vmcnt(8)
	s_waitcnt lgkmcnt(8)
	v_pk_mul_f32 v[230:231], v[136:137], v[230:231]
	v_pk_mul_f32 v[232:233], v[138:139], v[232:233]
	v_pk_mul_f32 v[244:245], v[120:121], v[128:129]
	v_pk_mul_f32 v[246:247], v[122:123], v[130:131]
	v_xor_b32_e32 v230, v252, v230
	v_xor_b32_e32 v231, v252, v231
	v_xor_b32_e32 v232, v252, v232
	v_xor_b32_e32 v233, v252, v233
	v_pk_add_f32 v[244:245], v[244:245], v[230:231]
	v_pk_add_f32 v[246:247], v[246:247], v[232:233]
	v_cndmask_b32_e64 v120, v120, v244, s[4:5]
	v_cndmask_b32_e64 v121, v121, v245, s[4:5]
	v_cndmask_b32_e64 v122, v122, v246, s[4:5]
	v_cndmask_b32_e64 v123, v123, v247, s[4:5]
	v_pk_mul_f32 v[234:235], v[140:141], v[234:235]
	v_pk_mul_f32 v[236:237], v[142:143], v[236:237]
	v_pk_mul_f32 v[244:245], v[124:125], v[132:133]
	v_pk_mul_f32 v[246:247], v[126:127], v[134:135]
	v_xor_b32_e32 v234, v252, v234
	v_xor_b32_e32 v235, v252, v235
	v_xor_b32_e32 v236, v252, v236
	v_xor_b32_e32 v237, v252, v237
	v_pk_add_f32 v[244:245], v[244:245], v[234:235]
	v_pk_add_f32 v[246:247], v[246:247], v[236:237]
	v_cndmask_b32_e64 v124, v124, v244, s[4:5]
	v_cndmask_b32_e64 v125, v125, v245, s[4:5]
	v_cndmask_b32_e64 v126, v126, v246, s[4:5]
	v_cndmask_b32_e64 v127, v127, v247, s[4:5]
	v_pk_mul_f32 v[120:121], v[120:121], s[28:29] op_sel_hi:[1,0]
	v_pk_mul_f32 v[122:123], v[122:123], s[28:29] op_sel_hi:[1,0]
	v_pk_mul_f32 v[124:125], v[124:125], s[28:29] op_sel_hi:[1,0]
	v_pk_mul_f32 v[126:127], v[126:127], s[28:29] op_sel_hi:[1,0]
	v_cvt_pk_bf16_f32 v248, v120, v121
	v_cvt_pk_bf16_f32 v249, v122, v123
	v_cvt_pk_bf16_f32 v250, v124, v125
	v_cvt_pk_bf16_f32 v251, v126, v127
	global_store_dwordx4 v169, v[248:251], s[26:27]
	s_nop 1
	ds_bpermute_b32 v230, v202, v112
	ds_bpermute_b32 v231, v202, v113
	ds_bpermute_b32 v232, v202, v114
	ds_bpermute_b32 v233, v202, v115
	ds_bpermute_b32 v234, v202, v116
	ds_bpermute_b32 v235, v202, v117
	ds_bpermute_b32 v236, v202, v118
	ds_bpermute_b32 v237, v202, v119
	s_waitcnt lgkmcnt(8)
	v_pk_mul_f32 v[196:197], v[136:137], v[196:197]
	v_pk_mul_f32 v[198:199], v[138:139], v[198:199]
	v_pk_mul_f32 v[244:245], v[56:57], v[128:129]
	v_pk_mul_f32 v[246:247], v[58:59], v[130:131]
	v_xor_b32_e32 v196, v252, v196
	v_xor_b32_e32 v197, v252, v197
	v_xor_b32_e32 v198, v252, v198
	v_xor_b32_e32 v199, v252, v199
	v_pk_add_f32 v[244:245], v[244:245], v[196:197]
	v_pk_add_f32 v[246:247], v[246:247], v[198:199]
	v_cndmask_b32_e64 v56, v56, v244, s[4:5]
	v_cndmask_b32_e64 v57, v57, v245, s[4:5]
	v_cndmask_b32_e64 v58, v58, v246, s[4:5]
	v_cndmask_b32_e64 v59, v59, v247, s[4:5]
	v_pk_mul_f32 v[156:157], v[140:141], v[156:157]
	v_pk_mul_f32 v[158:159], v[142:143], v[158:159]
	v_pk_mul_f32 v[244:245], v[60:61], v[132:133]
	v_pk_mul_f32 v[246:247], v[62:63], v[134:135]
	v_xor_b32_e32 v156, v252, v156
	v_xor_b32_e32 v157, v252, v157
	v_xor_b32_e32 v158, v252, v158
	v_xor_b32_e32 v159, v252, v159
	v_pk_add_f32 v[244:245], v[244:245], v[156:157]
	v_pk_add_f32 v[246:247], v[246:247], v[158:159]
	v_cndmask_b32_e64 v60, v60, v244, s[4:5]
	v_cndmask_b32_e64 v61, v61, v245, s[4:5]
	v_cndmask_b32_e64 v62, v62, v246, s[4:5]
	v_cndmask_b32_e64 v63, v63, v247, s[4:5]
	v_pk_mul_f32 v[56:57], v[56:57], s[28:29] op_sel_hi:[1,0]
	v_pk_mul_f32 v[58:59], v[58:59], s[28:29] op_sel_hi:[1,0]
	v_pk_mul_f32 v[60:61], v[60:61], s[28:29] op_sel_hi:[1,0]
	v_pk_mul_f32 v[62:63], v[62:63], s[28:29] op_sel_hi:[1,0]
	v_cvt_pk_bf16_f32 v248, v56, v57
	v_cvt_pk_bf16_f32 v249, v58, v59
	v_cvt_pk_bf16_f32 v250, v60, v61
	v_cvt_pk_bf16_f32 v251, v62, v63
	global_store_dwordx4 v169, v[248:251], s[98:99]
	s_nop 1
	s_add_u32 s26, s26, 0x800
	s_addc_u32 s27, s27, 0
	s_add_u32 s98, s98, 0x800
	s_addc_u32 s99, s99, 0
	global_load_dwordx4 v[128:131], v168, s[24:25] offset:3072
	global_load_dwordx4 v[132:135], v168, s[24:25] offset:3088
	global_load_dwordx4 v[136:139], v168, s[24:25] offset:3104
	global_load_dwordx4 v[140:143], v168, s[24:25] offset:3120
	s_add_u32 s24, s24, 0x2000
	s_addc_u32 s25, s25, 0
	ds_bpermute_b32 v196, v202, v48
	ds_bpermute_b32 v197, v202, v49
	ds_bpermute_b32 v198, v202, v50
	ds_bpermute_b32 v199, v202, v51
	ds_bpermute_b32 v156, v202, v52
	ds_bpermute_b32 v157, v202, v53
	ds_bpermute_b32 v158, v202, v54
	ds_bpermute_b32 v159, v202, v55
	s_waitcnt vmcnt(10)
; __device__ __forceinline__ unsigned cvt_pk_bf16(float lo, float hi) { const f32x2c v = {lo, hi}; const bf16x2c b = __builtin_convertvector(v, bf16x2c); return __builtin_bit_cast(unsigned, b); }
; #define PG8_GAS __attribute__((address_space(1)))
;     __device__ __forceinline__ void operator()(const f32x4 (&acc)[2][2][4][2], const Unit& u, int wr, int wc, int fr, int fq) const {
;     ...
;                         const int r = rbase + ai * HALF + m * 16; const int s = r & 8191;
;                         f32x4 v0 = acc[ai][bj][m][0], v1 = acc[ai][bj][m][1];
;                         if (rotw) {
;                             f32x4 p0, p1;
; #pragma unroll
;                             for (int j = 0; j < 4; ++j) { p0[j] = __shfl_xor(v0[j], 16); p1[j] = __shfl_xor(v1[j], 16); }
;                             if (fq < 2) {
;                                 const f32x4 c0 = *(const PG8_GAS f32x4*)(rope + (size_t)r * 16), c1 = *(const PG8_GAS f32x4*)(rope + (size_t)r * 16 + 4);
;                                 const f32x4 s0 = *(const PG8_GAS f32x4*)(rope + (size_t)r * 16 + 8), s1 = *(const PG8_GAS f32x4*)(rope + (size_t)r * 16 + 12);
;                                 if (fq == 0) { v0 = v0 * c0 - p0 * s0; v1 = v1 * c1 - p1 * s1; }
;                                 else { v0 = v0 * c0 + p0 * s0; v1 = v1 * c1 + p1 * s1; }
;                             }
;                         }
;                         if (seg == 0) { v0 = v0 * 0.18033688011112042f; v1 = v1 * 0.18033688011112042f; }
;                         u32x4 w; w.x = cvt_pk_bf16(v0[0], v0[1]); w.y = cvt_pk_bf16(v0[2], v0[3]); w.z = cvt_pk_bf16(v1[0], v1[1]); w.w = cvt_pk_bf16(v1[2], v1[3]);
;                         *(PG8_GAS u32x4*)(segp + ((size_t)((b * 8 + head) * 8192 + s)) * 64 + ch) = w;
	s_waitcnt lgkmcnt(8)
	v_pk_mul_f32 v[230:231], v[188:189], v[230:231]
	v_pk_mul_f32 v[232:233], v[190:191], v[232:233]
	v_pk_mul_f32 v[244:245], v[112:113], v[180:181]
	v_pk_mul_f32 v[246:247], v[114:115], v[182:183]
	v_xor_b32_e32 v230, v252, v230
	v_xor_b32_e32 v231, v252, v231
	v_xor_b32_e32 v232, v252, v232
	v_xor_b32_e32 v233, v252, v233
	v_pk_add_f32 v[244:245], v[244:245], v[230:231]
	v_pk_add_f32 v[246:247], v[246:247], v[232:233]
	v_cndmask_b32_e64 v112, v112, v244, s[4:5]
	v_cndmask_b32_e64 v113, v113, v245, s[4:5]
	v_cndmask_b32_e64 v114, v114, v246, s[4:5]
	v_cndmask_b32_e64 v115, v115, v247, s[4:5]
	v_pk_mul_f32 v[234:235], v[192:193], v[234:235]
	v_pk_mul_f32 v[236:237], v[194:195], v[236:237]
	v_pk_mul_f32 v[244:245], v[116:117], v[184:185]
	v_pk_mul_f32 v[246:247], v[118:119], v[186:187]
	v_xor_b32_e32 v234, v252, v234
	v_xor_b32_e32 v235, v252, v235
	v_xor_b32_e32 v236, v252, v236
	v_xor_b32_e32 v237, v252, v237
	v_pk_add_f32 v[244:245], v[244:245], v[234:235]
	v_pk_add_f32 v[246:247], v[246:247], v[236:237]
	v_cndmask_b32_e64 v116, v116, v244, s[4:5]
	v_cndmask_b32_e64 v117, v117, v245, s[4:5]
	v_cndmask_b32_e64 v118, v118, v246, s[4:5]
	v_cndmask_b32_e64 v119, v119, v247, s[4:5]
	v_pk_mul_f32 v[112:113], v[112:113], s[28:29] op_sel_hi:[1,0]
	v_pk_mul_f32 v[114:115], v[114:115], s[28:29] op_sel_hi:[1,0]
	v_pk_mul_f32 v[116:117], v[116:117], s[28:29] op_sel_hi:[1,0]
	v_pk_mul_f32 v[118:119], v[118:119], s[28:29] op_sel_hi:[1,0]
	v_cvt_pk_bf16_f32 v248, v112, v113
	v_cvt_pk_bf16_f32 v249, v114, v115
	v_cvt_pk_bf16_f32 v250, v116, v117
	v_cvt_pk_bf16_f32 v251, v118, v119
	global_store_dwordx4 v169, v[248:251], s[26:27]
	s_nop 1
	ds_bpermute_b32 v230, v202, v104
	ds_bpermute_b32 v231, v202, v105
	ds_bpermute_b32 v232, v202, v106
	ds_bpermute_b32 v233, v202, v107
	ds_bpermute_b32 v234, v202, v108
	ds_bpermute_b32 v235, v202, v109
	ds_bpermute_b32 v236, v202, v110
	ds_bpermute_b32 v237, v202, v111
	s_waitcnt lgkmcnt(8)
	v_pk_mul_f32 v[196:197], v[188:189], v[196:197]
	v_pk_mul_f32 v[198:199], v[190:191], v[198:199]
	v_pk_mul_f32 v[244:245], v[48:49], v[180:181]
	v_pk_mul_f32 v[246:247], v[50:51], v[182:183]
	v_xor_b32_e32 v196, v252, v196
	v_xor_b32_e32 v197, v252, v197
	v_xor_b32_e32 v198, v252, v198
	v_xor_b32_e32 v199, v252, v199
	v_pk_add_f32 v[244:245], v[244:245], v[196:197]
	v_pk_add_f32 v[246:247], v[246:247], v[198:199]
	v_cndmask_b32_e64 v48, v48, v244, s[4:5]
	v_cndmask_b32_e64 v49, v49, v245, s[4:5]
	v_cndmask_b32_e64 v50, v50, v246, s[4:5]
	v_cndmask_b32_e64 v51, v51, v247, s[4:5]
	v_pk_mul_f32 v[156:157], v[192:193], v[156:157]
	v_pk_mul_f32 v[158:159], v[194:195], v[158:159]
	v_pk_mul_f32 v[244:245], v[52:53], v[184:185]
	v_pk_mul_f32 v[246:247], v[54:55], v[186:187]
	v_xor_b32_e32 v156, v252, v156
	v_xor_b32_e32 v157, v252, v157
	v_xor_b32_e32 v158, v252, v158
	v_xor_b32_e32 v159, v252, v159
	v_pk_add_f32 v[244:245], v[244:245], v[156:157]
	v_pk_add_f32 v[246:247], v[246:247], v[158:159]
	v_cndmask_b32_e64 v52, v52, v244, s[4:5]
	v_cndmask_b32_e64 v53, v53, v245, s[4:5]
	v_cndmask_b32_e64 v54, v54, v246, s[4:5]
	v_cndmask_b32_e64 v55, v55, v247, s[4:5]
	v_pk_mul_f32 v[48:49], v[48:49], s[28:29] op_sel_hi:[1,0]
	v_pk_mul_f32 v[50:51], v[50:51], s[28:29] op_sel_hi:[1,0]
	v_pk_mul_f32 v[52:53], v[52:53], s[28:29] op_sel_hi:[1,0]
	v_pk_mul_f32 v[54:55], v[54:55], s[28:29] op_sel_hi:[1,0]
	v_cvt_pk_bf16_f32 v248, v48, v49
	v_cvt_pk_bf16_f32 v249, v50, v51
	v_cvt_pk_bf16_f32 v250, v52, v53
	v_cvt_pk_bf16_f32 v251, v54, v55
	global_store_dwordx4 v169, v[248:251], s[98:99]
	s_nop 1
	s_add_u32 s26, s26, 0x800
	s_addc_u32 s27, s27, 0
	s_add_u32 s98, s98, 0x800
	s_addc_u32 s99, s99, 0
	global_load_dwordx4 v[180:183], v168, s[24:25] offset:0
	global_load_dwordx4 v[184:187], v168, s[24:25] offset:16
	global_load_dwordx4 v[188:191], v168, s[24:25] offset:32
	global_load_dwordx4 v[192:195], v168, s[24:25] offset:48
	ds_bpermute_b32 v196, v202, v40
	ds_bpermute_b32 v197, v202, v41
	ds_bpermute_b32 v198, v202, v42
	ds_bpermute_b32 v199, v202, v43
	ds_bpermute_b32 v156, v202, v44
	ds_bpermute_b32 v157, v202, v45
	ds_bpermute_b32 v158, v202, v46
	ds_bpermute_b32 v159, v202, v47
	s_waitcnt vmcnt(12)
	s_waitcnt lgkmcnt(8)
	v_pk_mul_f32 v[230:231], v[222:223], v[230:231]
	v_pk_mul_f32 v[232:233], v[224:225], v[232:233]
	v_pk_mul_f32 v[244:245], v[104:105], v[214:215]
	v_pk_mul_f32 v[246:247], v[106:107], v[216:217]
	v_xor_b32_e32 v230, v252, v230
	v_xor_b32_e32 v231, v252, v231
	v_xor_b32_e32 v232, v252, v232
	v_xor_b32_e32 v233, v252, v233
	v_pk_add_f32 v[244:245], v[244:245], v[230:231]
	v_pk_add_f32 v[246:247], v[246:247], v[232:233]
	v_cndmask_b32_e64 v104, v104, v244, s[4:5]
	v_cndmask_b32_e64 v105, v105, v245, s[4:5]
	v_cndmask_b32_e64 v106, v106, v246, s[4:5]
	v_cndmask_b32_e64 v107, v107, v247, s[4:5]
	v_pk_mul_f32 v[234:235], v[226:227], v[234:235]
	v_pk_mul_f32 v[236:237], v[228:229], v[236:237]
	v_pk_mul_f32 v[244:245], v[108:109], v[218:219]
	v_pk_mul_f32 v[246:247], v[110:111], v[220:221]
	v_xor_b32_e32 v234, v252, v234
	v_xor_b32_e32 v235, v252, v235
	v_xor_b32_e32 v236, v252, v236
	v_xor_b32_e32 v237, v252, v237
	v_pk_add_f32 v[244:245], v[244:245], v[234:235]
	v_pk_add_f32 v[246:247], v[246:247], v[236:237]
	v_cndmask_b32_e64 v108, v108, v244, s[4:5]
	v_cndmask_b32_e64 v109, v109, v245, s[4:5]
	v_cndmask_b32_e64 v110, v110, v246, s[4:5]
	v_cndmask_b32_e64 v111, v111, v247, s[4:5]
	v_pk_mul_f32 v[104:105], v[104:105], s[28:29] op_sel_hi:[1,0]
	v_pk_mul_f32 v[106:107], v[106:107], s[28:29] op_sel_hi:[1,0]
	v_pk_mul_f32 v[108:109], v[108:109], s[28:29] op_sel_hi:[1,0]
	v_pk_mul_f32 v[110:111], v[110:111], s[28:29] op_sel_hi:[1,0]
	v_cvt_pk_bf16_f32 v248, v104, v105
	v_cvt_pk_bf16_f32 v249, v106, v107
	v_cvt_pk_bf16_f32 v250, v108, v109
	v_cvt_pk_bf16_f32 v251, v110, v111
	global_store_dwordx4 v169, v[248:251], s[26:27]
	s_nop 1
	ds_bpermute_b32 v230, v202, v96
	ds_bpermute_b32 v231, v202, v97
	ds_bpermute_b32 v232, v202, v98
	ds_bpermute_b32 v233, v202, v99
	ds_bpermute_b32 v234, v202, v100
	ds_bpermute_b32 v235, v202, v101
	ds_bpermute_b32 v236, v202, v102
	ds_bpermute_b32 v237, v202, v103
	s_waitcnt lgkmcnt(8)
; __device__ __forceinline__ unsigned cvt_pk_bf16(float lo, float hi) { const f32x2c v = {lo, hi}; const bf16x2c b = __builtin_convertvector(v, bf16x2c); return __builtin_bit_cast(unsigned, b); }
; #define PG8_GAS __attribute__((address_space(1)))
;     __device__ __forceinline__ void operator()(const f32x4 (&acc)[2][2][4][2], const Unit& u, int wr, int wc, int fr, int fq) const {
;     ...
;                         const int r = rbase + ai * HALF + m * 16; const int s = r & 8191;
;                         f32x4 v0 = acc[ai][bj][m][0], v1 = acc[ai][bj][m][1];
;                         if (rotw) {
;                             f32x4 p0, p1;
; #pragma unroll
;                             for (int j = 0; j < 4; ++j) { p0[j] = __shfl_xor(v0[j], 16); p1[j] = __shfl_xor(v1[j], 16); }
;                             if (fq < 2) {
;                                 const f32x4 c0 = *(const PG8_GAS f32x4*)(rope + (size_t)r * 16), c1 = *(const PG8_GAS f32x4*)(rope + (size_t)r * 16 + 4);
;                                 const f32x4 s0 = *(const PG8_GAS f32x4*)(rope + (size_t)r * 16 + 8), s1 = *(const PG8_GAS f32x4*)(rope + (size_t)r * 16 + 12);
;                                 if (fq == 0) { v0 = v0 * c0 - p0 * s0; v1 = v1 * c1 - p1 * s1; }
;                                 else { v0 = v0 * c0 + p0 * s0; v1 = v1 * c1 + p1 * s1; }
;                             }
;                         }
;                         if (seg == 0) { v0 = v0 * 0.18033688011112042f; v1 = v1 * 0.18033688011112042f; }
;                         u32x4 w; w.x = cvt_pk_bf16(v0[0], v0[1]); w.y = cvt_pk_bf16(v0[2], v0[3]); w.z = cvt_pk_bf16(v1[0], v1[1]); w.w = cvt_pk_bf16(v1[2], v1[3]);
;                         *(PG8_GAS u32x4*)(segp + ((size_t)((b * 8 + head) * 8192 + s)) * 64 + ch) = w;
	v_pk_mul_f32 v[196:197], v[222:223], v[196:197]
	v_pk_mul_f32 v[198:199], v[224:225], v[198:199]
	v_pk_mul_f32 v[244:245], v[40:41], v[214:215]
	v_pk_mul_f32 v[246:247], v[42:43], v[216:217]
	v_xor_b32_e32 v196, v252, v196
	v_xor_b32_e32 v197, v252, v197
	v_xor_b32_e32 v198, v252, v198
	v_xor_b32_e32 v199, v252, v199
	v_pk_add_f32 v[244:245], v[244:245], v[196:197]
	v_pk_add_f32 v[246:247], v[246:247], v[198:199]
	v_cndmask_b32_e64 v40, v40, v244, s[4:5]
	v_cndmask_b32_e64 v41, v41, v245, s[4:5]
	v_cndmask_b32_e64 v42, v42, v246, s[4:5]
	v_cndmask_b32_e64 v43, v43, v247, s[4:5]
	v_pk_mul_f32 v[156:157], v[226:227], v[156:157]
	v_pk_mul_f32 v[158:159], v[228:229], v[158:159]
	v_pk_mul_f32 v[244:245], v[44:45], v[218:219]
	v_pk_mul_f32 v[246:247], v[46:47], v[220:221]
	v_xor_b32_e32 v156, v252, v156
	v_xor_b32_e32 v157, v252, v157
	v_xor_b32_e32 v158, v252, v158
	v_xor_b32_e32 v159, v252, v159
	v_pk_add_f32 v[244:245], v[244:245], v[156:157]
	v_pk_add_f32 v[246:247], v[246:247], v[158:159]
	v_cndmask_b32_e64 v44, v44, v244, s[4:5]
	v_cndmask_b32_e64 v45, v45, v245, s[4:5]
	v_cndmask_b32_e64 v46, v46, v246, s[4:5]
	v_cndmask_b32_e64 v47, v47, v247, s[4:5]
	v_pk_mul_f32 v[40:41], v[40:41], s[28:29] op_sel_hi:[1,0]
	v_pk_mul_f32 v[42:43], v[42:43], s[28:29] op_sel_hi:[1,0]
	v_pk_mul_f32 v[44:45], v[44:45], s[28:29] op_sel_hi:[1,0]
	v_pk_mul_f32 v[46:47], v[46:47], s[28:29] op_sel_hi:[1,0]
	v_cvt_pk_bf16_f32 v248, v40, v41
	v_cvt_pk_bf16_f32 v249, v42, v43
	v_cvt_pk_bf16_f32 v250, v44, v45
	v_cvt_pk_bf16_f32 v251, v46, v47
	global_store_dwordx4 v169, v[248:251], s[98:99]
	s_nop 1
	s_add_u32 s26, s26, 0x800
	s_addc_u32 s27, s27, 0
	s_add_u32 s98, s98, 0x800
	s_addc_u32 s99, s99, 0
	global_load_dwordx4 v[214:217], v168, s[24:25] offset:1024
	global_load_dwordx4 v[218:221], v168, s[24:25] offset:1040
	global_load_dwordx4 v[222:225], v168, s[24:25] offset:1056
	global_load_dwordx4 v[226:229], v168, s[24:25] offset:1072
	ds_bpermute_b32 v196, v202, v32
	ds_bpermute_b32 v197, v202, v33
	ds_bpermute_b32 v198, v202, v34
	ds_bpermute_b32 v199, v202, v35
	ds_bpermute_b32 v156, v202, v36
	ds_bpermute_b32 v157, v202, v37
	ds_bpermute_b32 v158, v202, v38
	ds_bpermute_b32 v159, v202, v39
	s_waitcnt vmcnt(12)
	s_waitcnt lgkmcnt(8)
	v_pk_mul_f32 v[230:231], v[136:137], v[230:231]
	v_pk_mul_f32 v[232:233], v[138:139], v[232:233]
	v_pk_mul_f32 v[244:245], v[96:97], v[128:129]
	v_pk_mul_f32 v[246:247], v[98:99], v[130:131]
	v_xor_b32_e32 v230, v252, v230
	v_xor_b32_e32 v231, v252, v231
	v_xor_b32_e32 v232, v252, v232
	v_xor_b32_e32 v233, v252, v233
	v_pk_add_f32 v[244:245], v[244:245], v[230:231]
	v_pk_add_f32 v[246:247], v[246:247], v[232:233]
	v_cndmask_b32_e64 v96, v96, v244, s[4:5]
	v_cndmask_b32_e64 v97, v97, v245, s[4:5]
	v_cndmask_b32_e64 v98, v98, v246, s[4:5]
	v_cndmask_b32_e64 v99, v99, v247, s[4:5]
	v_pk_mul_f32 v[234:235], v[140:141], v[234:235]
	v_pk_mul_f32 v[236:237], v[142:143], v[236:237]
	v_pk_mul_f32 v[244:245], v[100:101], v[132:133]
	v_pk_mul_f32 v[246:247], v[102:103], v[134:135]
	v_xor_b32_e32 v234, v252, v234
	v_xor_b32_e32 v235, v252, v235
	v_xor_b32_e32 v236, v252, v236
	v_xor_b32_e32 v237, v252, v237
	v_pk_add_f32 v[244:245], v[244:245], v[234:235]
	v_pk_add_f32 v[246:247], v[246:247], v[236:237]
	v_cndmask_b32_e64 v100, v100, v244, s[4:5]
	v_cndmask_b32_e64 v101, v101, v245, s[4:5]
	v_cndmask_b32_e64 v102, v102, v246, s[4:5]
	v_cndmask_b32_e64 v103, v103, v247, s[4:5]
	v_pk_mul_f32 v[96:97], v[96:97], s[28:29] op_sel_hi:[1,0]
	v_pk_mul_f32 v[98:99], v[98:99], s[28:29] op_sel_hi:[1,0]
	v_pk_mul_f32 v[100:101], v[100:101], s[28:29] op_sel_hi:[1,0]
	v_pk_mul_f32 v[102:103], v[102:103], s[28:29] op_sel_hi:[1,0]
	v_cvt_pk_bf16_f32 v248, v96, v97
	v_cvt_pk_bf16_f32 v249, v98, v99
	v_cvt_pk_bf16_f32 v250, v100, v101
	v_cvt_pk_bf16_f32 v251, v102, v103
	global_store_dwordx4 v169, v[248:251], s[26:27]
	s_nop 1
	ds_bpermute_b32 v230, v202, v88
	ds_bpermute_b32 v231, v202, v89
	ds_bpermute_b32 v232, v202, v90
	ds_bpermute_b32 v233, v202, v91
	ds_bpermute_b32 v234, v202, v92
	ds_bpermute_b32 v235, v202, v93
	ds_bpermute_b32 v236, v202, v94
	ds_bpermute_b32 v237, v202, v95
	s_waitcnt lgkmcnt(8)
	v_pk_mul_f32 v[196:197], v[136:137], v[196:197]
	v_pk_mul_f32 v[198:199], v[138:139], v[198:199]
	v_pk_mul_f32 v[244:245], v[32:33], v[128:129]
	v_pk_mul_f32 v[246:247], v[34:35], v[130:131]
	v_xor_b32_e32 v196, v252, v196
	v_xor_b32_e32 v197, v252, v197
	v_xor_b32_e32 v198, v252, v198
	v_xor_b32_e32 v199, v252, v199
	v_pk_add_f32 v[244:245], v[244:245], v[196:197]
	v_pk_add_f32 v[246:247], v[246:247], v[198:199]
	v_cndmask_b32_e64 v32, v32, v244, s[4:5]
	v_cndmask_b32_e64 v33, v33, v245, s[4:5]
	v_cndmask_b32_e64 v34, v34, v246, s[4:5]
	v_cndmask_b32_e64 v35, v35, v247, s[4:5]
	v_pk_mul_f32 v[156:157], v[140:141], v[156:157]
	v_pk_mul_f32 v[158:159], v[142:143], v[158:159]
	v_pk_mul_f32 v[244:245], v[36:37], v[132:133]
	v_pk_mul_f32 v[246:247], v[38:39], v[134:135]
	v_xor_b32_e32 v156, v252, v156
	v_xor_b32_e32 v157, v252, v157
	v_xor_b32_e32 v158, v252, v158
	v_xor_b32_e32 v159, v252, v159
	v_pk_add_f32 v[244:245], v[244:245], v[156:157]
	v_pk_add_f32 v[246:247], v[246:247], v[158:159]
	v_cndmask_b32_e64 v36, v36, v244, s[4:5]
	v_cndmask_b32_e64 v37, v37, v245, s[4:5]
	v_cndmask_b32_e64 v38, v38, v246, s[4:5]
	v_cndmask_b32_e64 v39, v39, v247, s[4:5]
	v_pk_mul_f32 v[32:33], v[32:33], s[28:29] op_sel_hi:[1,0]
	v_pk_mul_f32 v[34:35], v[34:35], s[28:29] op_sel_hi:[1,0]
	v_pk_mul_f32 v[36:37], v[36:37], s[28:29] op_sel_hi:[1,0]
	v_pk_mul_f32 v[38:39], v[38:39], s[28:29] op_sel_hi:[1,0]
	v_cvt_pk_bf16_f32 v248, v32, v33
	v_cvt_pk_bf16_f32 v249, v34, v35
	v_cvt_pk_bf16_f32 v250, v36, v37
	v_cvt_pk_bf16_f32 v251, v38, v39
	global_store_dwordx4 v169, v[248:251], s[98:99]
	s_nop 1
	s_add_u32 s26, s26, 0x2800
	s_addc_u32 s27, s27, 0
	s_add_u32 s98, s98, 0x2800
	s_addc_u32 s99, s99, 0
	global_load_dwordx4 v[128:131], v168, s[24:25] offset:2048
	global_load_dwordx4 v[132:135], v168, s[24:25] offset:2064
	global_load_dwordx4 v[136:139], v168, s[24:25] offset:2080
	global_load_dwordx4 v[140:143], v168, s[24:25] offset:2096
	ds_bpermute_b32 v196, v202, v24
	ds_bpermute_b32 v197, v202, v25
	ds_bpermute_b32 v198, v202, v26
	ds_bpermute_b32 v199, v202, v27
	ds_bpermute_b32 v156, v202, v28
	ds_bpermute_b32 v157, v202, v29
	ds_bpermute_b32 v158, v202, v30
	ds_bpermute_b32 v159, v202, v31
	s_waitcnt vmcnt(12)
; __device__ __forceinline__ unsigned cvt_pk_bf16(float lo, float hi) { const f32x2c v = {lo, hi}; const bf16x2c b = __builtin_convertvector(v, bf16x2c); return __builtin_bit_cast(unsigned, b); }
; #define PG8_GAS __attribute__((address_space(1)))
;     __device__ __forceinline__ void operator()(const f32x4 (&acc)[2][2][4][2], const Unit& u, int wr, int wc, int fr, int fq) const {
;     ...
;                         const int r = rbase + ai * HALF + m * 16; const int s = r & 8191;
;                         f32x4 v0 = acc[ai][bj][m][0], v1 = acc[ai][bj][m][1];
;                         if (rotw) {
;                             f32x4 p0, p1;
; #pragma unroll
;                             for (int j = 0; j < 4; ++j) { p0[j] = __shfl_xor(v0[j], 16); p1[j] = __shfl_xor(v1[j], 16); }
;                             if (fq < 2) {
;                                 const f32x4 c0 = *(const PG8_GAS f32x4*)(rope + (size_t)r * 16), c1 = *(const PG8_GAS f32x4*)(rope + (size_t)r * 16 + 4);
;                                 const f32x4 s0 = *(const PG8_GAS f32x4*)(rope + (size_t)r * 16 + 8), s1 = *(const PG8_GAS f32x4*)(rope + (size_t)r * 16 + 12);
;                                 if (fq == 0) { v0 = v0 * c0 - p0 * s0; v1 = v1 * c1 - p1 * s1; }
;                                 else { v0 = v0 * c0 + p0 * s0; v1 = v1 * c1 + p1 * s1; }
;                             }
;                         }
;                         if (seg == 0) { v0 = v0 * 0.18033688011112042f; v1 = v1 * 0.18033688011112042f; }
;                         u32x4 w; w.x = cvt_pk_bf16(v0[0], v0[1]); w.y = cvt_pk_bf16(v0[2], v0[3]); w.z = cvt_pk_bf16(v1[0], v1[1]); w.w = cvt_pk_bf16(v1[2], v1[3]);
;                         *(PG8_GAS u32x4*)(segp + ((size_t)((b * 8 + head) * 8192 + s)) * 64 + ch) = w;
	s_waitcnt lgkmcnt(8)
	v_pk_mul_f32 v[230:231], v[188:189], v[230:231]
	v_pk_mul_f32 v[232:233], v[190:191], v[232:233]
	v_pk_mul_f32 v[244:245], v[88:89], v[180:181]
	v_pk_mul_f32 v[246:247], v[90:91], v[182:183]
	v_xor_b32_e32 v230, v252, v230
	v_xor_b32_e32 v231, v252, v231
	v_xor_b32_e32 v232, v252, v232
	v_xor_b32_e32 v233, v252, v233
	v_pk_add_f32 v[244:245], v[244:245], v[230:231]
	v_pk_add_f32 v[246:247], v[246:247], v[232:233]
	v_cndmask_b32_e64 v88, v88, v244, s[4:5]
	v_cndmask_b32_e64 v89, v89, v245, s[4:5]
	v_cndmask_b32_e64 v90, v90, v246, s[4:5]
	v_cndmask_b32_e64 v91, v91, v247, s[4:5]
	v_pk_mul_f32 v[234:235], v[192:193], v[234:235]
	v_pk_mul_f32 v[236:237], v[194:195], v[236:237]
	v_pk_mul_f32 v[244:245], v[92:93], v[184:185]
	v_pk_mul_f32 v[246:247], v[94:95], v[186:187]
	v_xor_b32_e32 v234, v252, v234
	v_xor_b32_e32 v235, v252, v235
	v_xor_b32_e32 v236, v252, v236
	v_xor_b32_e32 v237, v252, v237
	v_pk_add_f32 v[244:245], v[244:245], v[234:235]
	v_pk_add_f32 v[246:247], v[246:247], v[236:237]
	v_cndmask_b32_e64 v92, v92, v244, s[4:5]
	v_cndmask_b32_e64 v93, v93, v245, s[4:5]
	v_cndmask_b32_e64 v94, v94, v246, s[4:5]
	v_cndmask_b32_e64 v95, v95, v247, s[4:5]
	v_pk_mul_f32 v[88:89], v[88:89], s[28:29] op_sel_hi:[1,0]
	v_pk_mul_f32 v[90:91], v[90:91], s[28:29] op_sel_hi:[1,0]
	v_pk_mul_f32 v[92:93], v[92:93], s[28:29] op_sel_hi:[1,0]
	v_pk_mul_f32 v[94:95], v[94:95], s[28:29] op_sel_hi:[1,0]
	v_cvt_pk_bf16_f32 v248, v88, v89
	v_cvt_pk_bf16_f32 v249, v90, v91
	v_cvt_pk_bf16_f32 v250, v92, v93
	v_cvt_pk_bf16_f32 v251, v94, v95
	global_store_dwordx4 v169, v[248:251], s[26:27]
	s_nop 1
	ds_bpermute_b32 v230, v202, v80
	ds_bpermute_b32 v231, v202, v81
	ds_bpermute_b32 v232, v202, v82
	ds_bpermute_b32 v233, v202, v83
	ds_bpermute_b32 v234, v202, v84
	ds_bpermute_b32 v235, v202, v85
	ds_bpermute_b32 v236, v202, v86
	ds_bpermute_b32 v237, v202, v87
	s_waitcnt lgkmcnt(8)
	v_pk_mul_f32 v[196:197], v[188:189], v[196:197]
	v_pk_mul_f32 v[198:199], v[190:191], v[198:199]
	v_pk_mul_f32 v[244:245], v[24:25], v[180:181]
	v_pk_mul_f32 v[246:247], v[26:27], v[182:183]
	v_xor_b32_e32 v196, v252, v196
	v_xor_b32_e32 v197, v252, v197
	v_xor_b32_e32 v198, v252, v198
	v_xor_b32_e32 v199, v252, v199
	v_pk_add_f32 v[244:245], v[244:245], v[196:197]
	v_pk_add_f32 v[246:247], v[246:247], v[198:199]
	v_cndmask_b32_e64 v24, v24, v244, s[4:5]
	v_cndmask_b32_e64 v25, v25, v245, s[4:5]
	v_cndmask_b32_e64 v26, v26, v246, s[4:5]
	v_cndmask_b32_e64 v27, v27, v247, s[4:5]
	v_pk_mul_f32 v[156:157], v[192:193], v[156:157]
	v_pk_mul_f32 v[158:159], v[194:195], v[158:159]
	v_pk_mul_f32 v[244:245], v[28:29], v[184:185]
	v_pk_mul_f32 v[246:247], v[30:31], v[186:187]
	v_xor_b32_e32 v156, v252, v156
	v_xor_b32_e32 v157, v252, v157
	v_xor_b32_e32 v158, v252, v158
	v_xor_b32_e32 v159, v252, v159
	v_pk_add_f32 v[244:245], v[244:245], v[156:157]
	v_pk_add_f32 v[246:247], v[246:247], v[158:159]
	v_cndmask_b32_e64 v28, v28, v244, s[4:5]
	v_cndmask_b32_e64 v29, v29, v245, s[4:5]
	v_cndmask_b32_e64 v30, v30, v246, s[4:5]
	v_cndmask_b32_e64 v31, v31, v247, s[4:5]
	v_pk_mul_f32 v[24:25], v[24:25], s[28:29] op_sel_hi:[1,0]
	v_pk_mul_f32 v[26:27], v[26:27], s[28:29] op_sel_hi:[1,0]
	v_pk_mul_f32 v[28:29], v[28:29], s[28:29] op_sel_hi:[1,0]
	v_pk_mul_f32 v[30:31], v[30:31], s[28:29] op_sel_hi:[1,0]
	v_cvt_pk_bf16_f32 v248, v24, v25
	v_cvt_pk_bf16_f32 v249, v26, v27
	v_cvt_pk_bf16_f32 v250, v28, v29
	v_cvt_pk_bf16_f32 v251, v30, v31
	global_store_dwordx4 v169, v[248:251], s[98:99]
	s_nop 1
	s_add_u32 s26, s26, 0x800
	s_addc_u32 s27, s27, 0
	s_add_u32 s98, s98, 0x800
	s_addc_u32 s99, s99, 0
	global_load_dwordx4 v[180:183], v168, s[24:25] offset:3072
	global_load_dwordx4 v[184:187], v168, s[24:25] offset:3088
	global_load_dwordx4 v[188:191], v168, s[24:25] offset:3104
	global_load_dwordx4 v[192:195], v168, s[24:25] offset:3120
	ds_bpermute_b32 v196, v202, v16
	ds_bpermute_b32 v197, v202, v17
	ds_bpermute_b32 v198, v202, v18
	ds_bpermute_b32 v199, v202, v19
	ds_bpermute_b32 v156, v202, v20
	ds_bpermute_b32 v157, v202, v21
	ds_bpermute_b32 v158, v202, v22
	ds_bpermute_b32 v159, v202, v23
	s_waitcnt vmcnt(12)
	s_waitcnt lgkmcnt(8)
	v_pk_mul_f32 v[230:231], v[222:223], v[230:231]
	v_pk_mul_f32 v[232:233], v[224:225], v[232:233]
	v_pk_mul_f32 v[244:245], v[80:81], v[214:215]
	v_pk_mul_f32 v[246:247], v[82:83], v[216:217]
	v_xor_b32_e32 v230, v252, v230
	v_xor_b32_e32 v231, v252, v231
	v_xor_b32_e32 v232, v252, v232
	v_xor_b32_e32 v233, v252, v233
	v_pk_add_f32 v[244:245], v[244:245], v[230:231]
	v_pk_add_f32 v[246:247], v[246:247], v[232:233]
	v_cndmask_b32_e64 v80, v80, v244, s[4:5]
	v_cndmask_b32_e64 v81, v81, v245, s[4:5]
	v_cndmask_b32_e64 v82, v82, v246, s[4:5]
	v_cndmask_b32_e64 v83, v83, v247, s[4:5]
	v_pk_mul_f32 v[234:235], v[226:227], v[234:235]
	v_pk_mul_f32 v[236:237], v[228:229], v[236:237]
	v_pk_mul_f32 v[244:245], v[84:85], v[218:219]
	v_pk_mul_f32 v[246:247], v[86:87], v[220:221]
	v_xor_b32_e32 v234, v252, v234
	v_xor_b32_e32 v235, v252, v235
	v_xor_b32_e32 v236, v252, v236
	v_xor_b32_e32 v237, v252, v237
	v_pk_add_f32 v[244:245], v[244:245], v[234:235]
	v_pk_add_f32 v[246:247], v[246:247], v[236:237]
	v_cndmask_b32_e64 v84, v84, v244, s[4:5]
	v_cndmask_b32_e64 v85, v85, v245, s[4:5]
	v_cndmask_b32_e64 v86, v86, v246, s[4:5]
	v_cndmask_b32_e64 v87, v87, v247, s[4:5]
	v_pk_mul_f32 v[80:81], v[80:81], s[28:29] op_sel_hi:[1,0]
	v_pk_mul_f32 v[82:83], v[82:83], s[28:29] op_sel_hi:[1,0]
	v_pk_mul_f32 v[84:85], v[84:85], s[28:29] op_sel_hi:[1,0]
	v_pk_mul_f32 v[86:87], v[86:87], s[28:29] op_sel_hi:[1,0]
	v_cvt_pk_bf16_f32 v248, v80, v81
	v_cvt_pk_bf16_f32 v249, v82, v83
	v_cvt_pk_bf16_f32 v250, v84, v85
	v_cvt_pk_bf16_f32 v251, v86, v87
	global_store_dwordx4 v169, v[248:251], s[26:27]
	s_nop 1
	ds_bpermute_b32 v230, v202, v72
	ds_bpermute_b32 v231, v202, v73
	ds_bpermute_b32 v232, v202, v74
	ds_bpermute_b32 v233, v202, v75
	ds_bpermute_b32 v234, v202, v76
	ds_bpermute_b32 v235, v202, v77
	ds_bpermute_b32 v236, v202, v78
	ds_bpermute_b32 v237, v202, v79
	s_waitcnt lgkmcnt(8)
; __device__ __forceinline__ unsigned cvt_pk_bf16(float lo, float hi) { const f32x2c v = {lo, hi}; const bf16x2c b = __builtin_convertvector(v, bf16x2c); return __builtin_bit_cast(unsigned, b); }
; #define PG8_GAS __attribute__((address_space(1)))
;     __device__ __forceinline__ void operator()(const f32x4 (&acc)[2][2][4][2], const Unit& u, int wr, int wc, int fr, int fq) const {
;     ...
;                         const int r = rbase + ai * HALF + m * 16; const int s = r & 8191;
;                         f32x4 v0 = acc[ai][bj][m][0], v1 = acc[ai][bj][m][1];
;                         if (rotw) {
;                             f32x4 p0, p1;
; #pragma unroll
;                             for (int j = 0; j < 4; ++j) { p0[j] = __shfl_xor(v0[j], 16); p1[j] = __shfl_xor(v1[j], 16); }
;                             if (fq < 2) {
;                                 const f32x4 c0 = *(const PG8_GAS f32x4*)(rope + (size_t)r * 16), c1 = *(const PG8_GAS f32x4*)(rope + (size_t)r * 16 + 4);
;                                 const f32x4 s0 = *(const PG8_GAS f32x4*)(rope + (size_t)r * 16 + 8), s1 = *(const PG8_GAS f32x4*)(rope + (size_t)r * 16 + 12);
;                                 if (fq == 0) { v0 = v0 * c0 - p0 * s0; v1 = v1 * c1 - p1 * s1; }
;                                 else { v0 = v0 * c0 + p0 * s0; v1 = v1 * c1 + p1 * s1; }
;                             }
;                         }
;                         if (seg == 0) { v0 = v0 * 0.18033688011112042f; v1 = v1 * 0.18033688011112042f; }
;                         u32x4 w; w.x = cvt_pk_bf16(v0[0], v0[1]); w.y = cvt_pk_bf16(v0[2], v0[3]); w.z = cvt_pk_bf16(v1[0], v1[1]); w.w = cvt_pk_bf16(v1[2], v1[3]);
;                         *(PG8_GAS u32x4*)(segp + ((size_t)((b * 8 + head) * 8192 + s)) * 64 + ch) = w;
	v_pk_mul_f32 v[196:197], v[222:223], v[196:197]
	v_pk_mul_f32 v[198:199], v[224:225], v[198:199]
	v_pk_mul_f32 v[244:245], v[16:17], v[214:215]
	v_pk_mul_f32 v[246:247], v[18:19], v[216:217]
	v_xor_b32_e32 v196, v252, v196
	v_xor_b32_e32 v197, v252, v197
	v_xor_b32_e32 v198, v252, v198
	v_xor_b32_e32 v199, v252, v199
	v_pk_add_f32 v[244:245], v[244:245], v[196:197]
	v_pk_add_f32 v[246:247], v[246:247], v[198:199]
	v_cndmask_b32_e64 v16, v16, v244, s[4:5]
	v_cndmask_b32_e64 v17, v17, v245, s[4:5]
	v_cndmask_b32_e64 v18, v18, v246, s[4:5]
	v_cndmask_b32_e64 v19, v19, v247, s[4:5]
	v_pk_mul_f32 v[156:157], v[226:227], v[156:157]
	v_pk_mul_f32 v[158:159], v[228:229], v[158:159]
	v_pk_mul_f32 v[244:245], v[20:21], v[218:219]
	v_pk_mul_f32 v[246:247], v[22:23], v[220:221]
	v_xor_b32_e32 v156, v252, v156
	v_xor_b32_e32 v157, v252, v157
	v_xor_b32_e32 v158, v252, v158
	v_xor_b32_e32 v159, v252, v159
	v_pk_add_f32 v[244:245], v[244:245], v[156:157]
	v_pk_add_f32 v[246:247], v[246:247], v[158:159]
	v_cndmask_b32_e64 v20, v20, v244, s[4:5]
	v_cndmask_b32_e64 v21, v21, v245, s[4:5]
	v_cndmask_b32_e64 v22, v22, v246, s[4:5]
	v_cndmask_b32_e64 v23, v23, v247, s[4:5]
	v_pk_mul_f32 v[16:17], v[16:17], s[28:29] op_sel_hi:[1,0]
	v_pk_mul_f32 v[18:19], v[18:19], s[28:29] op_sel_hi:[1,0]
	v_pk_mul_f32 v[20:21], v[20:21], s[28:29] op_sel_hi:[1,0]
	v_pk_mul_f32 v[22:23], v[22:23], s[28:29] op_sel_hi:[1,0]
	v_cvt_pk_bf16_f32 v248, v16, v17
	v_cvt_pk_bf16_f32 v249, v18, v19
	v_cvt_pk_bf16_f32 v250, v20, v21
	v_cvt_pk_bf16_f32 v251, v22, v23
	global_store_dwordx4 v169, v[248:251], s[98:99]
	s_nop 1
	s_add_u32 s26, s26, 0x800
	s_addc_u32 s27, s27, 0
	s_add_u32 s98, s98, 0x800
	s_addc_u32 s99, s99, 0
	ds_bpermute_b32 v196, v202, v8
	ds_bpermute_b32 v197, v202, v9
	ds_bpermute_b32 v198, v202, v10
	ds_bpermute_b32 v199, v202, v11
	ds_bpermute_b32 v156, v202, v12
	ds_bpermute_b32 v157, v202, v13
	ds_bpermute_b32 v158, v202, v14
	ds_bpermute_b32 v159, v202, v15
	s_waitcnt vmcnt(8)
	s_waitcnt lgkmcnt(8)
	v_pk_mul_f32 v[230:231], v[136:137], v[230:231]
	v_pk_mul_f32 v[232:233], v[138:139], v[232:233]
	v_pk_mul_f32 v[244:245], v[72:73], v[128:129]
	v_pk_mul_f32 v[246:247], v[74:75], v[130:131]
	v_xor_b32_e32 v230, v252, v230
	v_xor_b32_e32 v231, v252, v231
	v_xor_b32_e32 v232, v252, v232
	v_xor_b32_e32 v233, v252, v233
	v_pk_add_f32 v[244:245], v[244:245], v[230:231]
	v_pk_add_f32 v[246:247], v[246:247], v[232:233]
	v_cndmask_b32_e64 v72, v72, v244, s[4:5]
	v_cndmask_b32_e64 v73, v73, v245, s[4:5]
	v_cndmask_b32_e64 v74, v74, v246, s[4:5]
	v_cndmask_b32_e64 v75, v75, v247, s[4:5]
	v_pk_mul_f32 v[234:235], v[140:141], v[234:235]
	v_pk_mul_f32 v[236:237], v[142:143], v[236:237]
	v_pk_mul_f32 v[244:245], v[76:77], v[132:133]
	v_pk_mul_f32 v[246:247], v[78:79], v[134:135]
	v_xor_b32_e32 v234, v252, v234
	v_xor_b32_e32 v235, v252, v235
	v_xor_b32_e32 v236, v252, v236
	v_xor_b32_e32 v237, v252, v237
	v_pk_add_f32 v[244:245], v[244:245], v[234:235]
	v_pk_add_f32 v[246:247], v[246:247], v[236:237]
	v_cndmask_b32_e64 v76, v76, v244, s[4:5]
	v_cndmask_b32_e64 v77, v77, v245, s[4:5]
	v_cndmask_b32_e64 v78, v78, v246, s[4:5]
	v_cndmask_b32_e64 v79, v79, v247, s[4:5]
	v_pk_mul_f32 v[72:73], v[72:73], s[28:29] op_sel_hi:[1,0]
	v_pk_mul_f32 v[74:75], v[74:75], s[28:29] op_sel_hi:[1,0]
	v_pk_mul_f32 v[76:77], v[76:77], s[28:29] op_sel_hi:[1,0]
	v_pk_mul_f32 v[78:79], v[78:79], s[28:29] op_sel_hi:[1,0]
	v_cvt_pk_bf16_f32 v248, v72, v73
	v_cvt_pk_bf16_f32 v249, v74, v75
	v_cvt_pk_bf16_f32 v250, v76, v77
	v_cvt_pk_bf16_f32 v251, v78, v79
	global_store_dwordx4 v169, v[248:251], s[26:27]
	s_nop 1
	ds_bpermute_b32 v230, v202, v64
	ds_bpermute_b32 v231, v202, v65
	ds_bpermute_b32 v232, v202, v66
	ds_bpermute_b32 v233, v202, v67
	ds_bpermute_b32 v234, v202, v68
	ds_bpermute_b32 v235, v202, v69
	ds_bpermute_b32 v236, v202, v70
	ds_bpermute_b32 v237, v202, v71
	s_waitcnt lgkmcnt(8)
	v_pk_mul_f32 v[196:197], v[136:137], v[196:197]
	v_pk_mul_f32 v[198:199], v[138:139], v[198:199]
	v_pk_mul_f32 v[244:245], v[8:9], v[128:129]
	v_pk_mul_f32 v[246:247], v[10:11], v[130:131]
	v_xor_b32_e32 v196, v252, v196
	v_xor_b32_e32 v197, v252, v197
	v_xor_b32_e32 v198, v252, v198
	v_xor_b32_e32 v199, v252, v199
	v_pk_add_f32 v[244:245], v[244:245], v[196:197]
	v_pk_add_f32 v[246:247], v[246:247], v[198:199]
	v_cndmask_b32_e64 v8, v8, v244, s[4:5]
	v_cndmask_b32_e64 v9, v9, v245, s[4:5]
	v_cndmask_b32_e64 v10, v10, v246, s[4:5]
	v_cndmask_b32_e64 v11, v11, v247, s[4:5]
	v_pk_mul_f32 v[156:157], v[140:141], v[156:157]
	v_pk_mul_f32 v[158:159], v[142:143], v[158:159]
	v_pk_mul_f32 v[244:245], v[12:13], v[132:133]
	v_pk_mul_f32 v[246:247], v[14:15], v[134:135]
	v_xor_b32_e32 v156, v252, v156
	v_xor_b32_e32 v157, v252, v157
	v_xor_b32_e32 v158, v252, v158
	v_xor_b32_e32 v159, v252, v159
	v_pk_add_f32 v[244:245], v[244:245], v[156:157]
	v_pk_add_f32 v[246:247], v[246:247], v[158:159]
	v_cndmask_b32_e64 v12, v12, v244, s[4:5]
	v_cndmask_b32_e64 v13, v13, v245, s[4:5]
	v_cndmask_b32_e64 v14, v14, v246, s[4:5]
	v_cndmask_b32_e64 v15, v15, v247, s[4:5]
	v_pk_mul_f32 v[8:9], v[8:9], s[28:29] op_sel_hi:[1,0]
	v_pk_mul_f32 v[10:11], v[10:11], s[28:29] op_sel_hi:[1,0]
	v_pk_mul_f32 v[12:13], v[12:13], s[28:29] op_sel_hi:[1,0]
	v_pk_mul_f32 v[14:15], v[14:15], s[28:29] op_sel_hi:[1,0]
	v_cvt_pk_bf16_f32 v248, v8, v9
	v_cvt_pk_bf16_f32 v249, v10, v11
	v_cvt_pk_bf16_f32 v250, v12, v13
	v_cvt_pk_bf16_f32 v251, v14, v15
	global_store_dwordx4 v169, v[248:251], s[98:99]
	s_nop 1
	s_add_u32 s26, s26, 0x800
	s_addc_u32 s27, s27, 0
	s_add_u32 s98, s98, 0x800
	s_addc_u32 s99, s99, 0
	ds_bpermute_b32 v196, v202, v4
	ds_bpermute_b32 v197, v202, v5
	ds_bpermute_b32 v198, v202, v6
	ds_bpermute_b32 v199, v202, v7
	ds_bpermute_b32 v156, v202, v0
	ds_bpermute_b32 v157, v202, v1
	ds_bpermute_b32 v158, v202, v2
	ds_bpermute_b32 v159, v202, v3
	s_waitcnt vmcnt(4)
; __device__ __forceinline__ unsigned cvt_pk_bf16(float lo, float hi) { const f32x2c v = {lo, hi}; const bf16x2c b = __builtin_convertvector(v, bf16x2c); return __builtin_bit_cast(unsigned, b); }
; #define PG8_GAS __attribute__((address_space(1)))
;     __device__ __forceinline__ void operator()(const f32x4 (&acc)[2][2][4][2], const Unit& u, int wr, int wc, int fr, int fq) const {
;     ...
;                         const int r = rbase + ai * HALF + m * 16; const int s = r & 8191;
;                         f32x4 v0 = acc[ai][bj][m][0], v1 = acc[ai][bj][m][1];
;                         if (rotw) {
;                             f32x4 p0, p1;
; #pragma unroll
;                             for (int j = 0; j < 4; ++j) { p0[j] = __shfl_xor(v0[j], 16); p1[j] = __shfl_xor(v1[j], 16); }
;                             if (fq < 2) {
;                                 const f32x4 c0 = *(const PG8_GAS f32x4*)(rope + (size_t)r * 16), c1 = *(const PG8_GAS f32x4*)(rope + (size_t)r * 16 + 4);
;                                 const f32x4 s0 = *(const PG8_GAS f32x4*)(rope + (size_t)r * 16 + 8), s1 = *(const PG8_GAS f32x4*)(rope + (size_t)r * 16 + 12);
;                                 if (fq == 0) { v0 = v0 * c0 - p0 * s0; v1 = v1 * c1 - p1 * s1; }
;                                 else { v0 = v0 * c0 + p0 * s0; v1 = v1 * c1 + p1 * s1; }
;                             }
;                         }
;                         if (seg == 0) { v0 = v0 * 0.18033688011112042f; v1 = v1 * 0.18033688011112042f; }
;                         u32x4 w; w.x = cvt_pk_bf16(v0[0], v0[1]); w.y = cvt_pk_bf16(v0[2], v0[3]); w.z = cvt_pk_bf16(v1[0], v1[1]); w.w = cvt_pk_bf16(v1[2], v1[3]);
;                         *(PG8_GAS u32x4*)(segp + ((size_t)((b * 8 + head) * 8192 + s)) * 64 + ch) = w;
	s_waitcnt lgkmcnt(8)
	v_pk_mul_f32 v[230:231], v[188:189], v[230:231]
	v_pk_mul_f32 v[232:233], v[190:191], v[232:233]
	v_pk_mul_f32 v[244:245], v[64:65], v[180:181]
	v_pk_mul_f32 v[246:247], v[66:67], v[182:183]
	v_xor_b32_e32 v230, v252, v230
	v_xor_b32_e32 v231, v252, v231
	v_xor_b32_e32 v232, v252, v232
	v_xor_b32_e32 v233, v252, v233
	v_pk_add_f32 v[244:245], v[244:245], v[230:231]
	v_pk_add_f32 v[246:247], v[246:247], v[232:233]
	v_cndmask_b32_e64 v64, v64, v244, s[4:5]
	v_cndmask_b32_e64 v65, v65, v245, s[4:5]
	v_cndmask_b32_e64 v66, v66, v246, s[4:5]
	v_cndmask_b32_e64 v67, v67, v247, s[4:5]
	v_pk_mul_f32 v[234:235], v[192:193], v[234:235]
	v_pk_mul_f32 v[236:237], v[194:195], v[236:237]
	v_pk_mul_f32 v[244:245], v[68:69], v[184:185]
	v_pk_mul_f32 v[246:247], v[70:71], v[186:187]
	v_xor_b32_e32 v234, v252, v234
	v_xor_b32_e32 v235, v252, v235
	v_xor_b32_e32 v236, v252, v236
	v_xor_b32_e32 v237, v252, v237
	v_pk_add_f32 v[244:245], v[244:245], v[234:235]
	v_pk_add_f32 v[246:247], v[246:247], v[236:237]
	v_cndmask_b32_e64 v68, v68, v244, s[4:5]
	v_cndmask_b32_e64 v69, v69, v245, s[4:5]
	v_cndmask_b32_e64 v70, v70, v246, s[4:5]
	v_cndmask_b32_e64 v71, v71, v247, s[4:5]
	v_pk_mul_f32 v[64:65], v[64:65], s[28:29] op_sel_hi:[1,0]
	v_pk_mul_f32 v[66:67], v[66:67], s[28:29] op_sel_hi:[1,0]
	v_pk_mul_f32 v[68:69], v[68:69], s[28:29] op_sel_hi:[1,0]
	v_pk_mul_f32 v[70:71], v[70:71], s[28:29] op_sel_hi:[1,0]
	v_cvt_pk_bf16_f32 v248, v64, v65
	v_cvt_pk_bf16_f32 v249, v66, v67
	v_cvt_pk_bf16_f32 v250, v68, v69
	v_cvt_pk_bf16_f32 v251, v70, v71
	global_store_dwordx4 v169, v[248:251], s[26:27]
	s_nop 1
	s_waitcnt lgkmcnt(0)
	v_pk_mul_f32 v[196:197], v[188:189], v[196:197]
	v_pk_mul_f32 v[198:199], v[190:191], v[198:199]
	v_pk_mul_f32 v[244:245], v[4:5], v[180:181]
	v_pk_mul_f32 v[246:247], v[6:7], v[182:183]
	v_xor_b32_e32 v196, v252, v196
	v_xor_b32_e32 v197, v252, v197
	v_xor_b32_e32 v198, v252, v198
	v_xor_b32_e32 v199, v252, v199
	v_pk_add_f32 v[244:245], v[244:245], v[196:197]
	v_pk_add_f32 v[246:247], v[246:247], v[198:199]
	v_cndmask_b32_e64 v4, v4, v244, s[4:5]
	v_cndmask_b32_e64 v5, v5, v245, s[4:5]
	v_cndmask_b32_e64 v6, v6, v246, s[4:5]
	v_cndmask_b32_e64 v7, v7, v247, s[4:5]
	v_pk_mul_f32 v[156:157], v[192:193], v[156:157]
	v_pk_mul_f32 v[158:159], v[194:195], v[158:159]
	v_pk_mul_f32 v[244:245], v[0:1], v[184:185]
	v_pk_mul_f32 v[246:247], v[2:3], v[186:187]
	v_xor_b32_e32 v156, v252, v156
	v_xor_b32_e32 v157, v252, v157
	v_xor_b32_e32 v158, v252, v158
	v_xor_b32_e32 v159, v252, v159
	v_pk_add_f32 v[244:245], v[244:245], v[156:157]
	v_pk_add_f32 v[246:247], v[246:247], v[158:159]
	v_cndmask_b32_e64 v0, v0, v244, s[4:5]
	v_cndmask_b32_e64 v1, v1, v245, s[4:5]
	v_cndmask_b32_e64 v2, v2, v246, s[4:5]
	v_cndmask_b32_e64 v3, v3, v247, s[4:5]
	v_pk_mul_f32 v[4:5], v[4:5], s[28:29] op_sel_hi:[1,0]
	v_pk_mul_f32 v[6:7], v[6:7], s[28:29] op_sel_hi:[1,0]
	v_pk_mul_f32 v[0:1], v[0:1], s[28:29] op_sel_hi:[1,0]
	v_pk_mul_f32 v[2:3], v[2:3], s[28:29] op_sel_hi:[1,0]
	v_cvt_pk_bf16_f32 v248, v4, v5
	v_cvt_pk_bf16_f32 v249, v6, v7
	v_cvt_pk_bf16_f32 v250, v0, v1
	v_cvt_pk_bf16_f32 v251, v2, v3
	global_store_dwordx4 v169, v[248:251], s[98:99]
	s_nop 1
	s_branch .Lrope_done
.Lrope_plain:
	v_pk_mul_f32 v[120:121], v[120:121], s[28:29] op_sel_hi:[1,0]
	v_pk_mul_f32 v[122:123], v[122:123], s[28:29] op_sel_hi:[1,0]
	v_pk_mul_f32 v[124:125], v[124:125], s[28:29] op_sel_hi:[1,0]
	v_pk_mul_f32 v[126:127], v[126:127], s[28:29] op_sel_hi:[1,0]
	v_cvt_pk_bf16_f32 v248, v120, v121
	v_cvt_pk_bf16_f32 v249, v122, v123
	v_cvt_pk_bf16_f32 v250, v124, v125
	v_cvt_pk_bf16_f32 v251, v126, v127
	global_store_dwordx4 v169, v[248:251], s[26:27]
	v_pk_mul_f32 v[56:57], v[56:57], s[28:29] op_sel_hi:[1,0]
	v_pk_mul_f32 v[58:59], v[58:59], s[28:29] op_sel_hi:[1,0]
	v_pk_mul_f32 v[60:61], v[60:61], s[28:29] op_sel_hi:[1,0]
	v_pk_mul_f32 v[62:63], v[62:63], s[28:29] op_sel_hi:[1,0]
	v_cvt_pk_bf16_f32 v244, v56, v57
	v_cvt_pk_bf16_f32 v245, v58, v59
	v_cvt_pk_bf16_f32 v246, v60, v61
	v_cvt_pk_bf16_f32 v247, v62, v63
	global_store_dwordx4 v169, v[244:247], s[98:99]
	s_add_u32 s26, s26, 0x800
	s_addc_u32 s27, s27, 0
	s_add_u32 s98, s98, 0x800
	s_addc_u32 s99, s99, 0
	v_pk_mul_f32 v[112:113], v[112:113], s[28:29] op_sel_hi:[1,0]
	v_pk_mul_f32 v[114:115], v[114:115], s[28:29] op_sel_hi:[1,0]
	v_pk_mul_f32 v[116:117], v[116:117], s[28:29] op_sel_hi:[1,0]
	v_pk_mul_f32 v[118:119], v[118:119], s[28:29] op_sel_hi:[1,0]
	v_cvt_pk_bf16_f32 v248, v112, v113
	v_cvt_pk_bf16_f32 v249, v114, v115
	v_cvt_pk_bf16_f32 v250, v116, v117
	v_cvt_pk_bf16_f32 v251, v118, v119
	global_store_dwordx4 v169, v[248:251], s[26:27]
	v_pk_mul_f32 v[48:49], v[48:49], s[28:29] op_sel_hi:[1,0]
	v_pk_mul_f32 v[50:51], v[50:51], s[28:29] op_sel_hi:[1,0]
	v_pk_mul_f32 v[52:53], v[52:53], s[28:29] op_sel_hi:[1,0]
	v_pk_mul_f32 v[54:55], v[54:55], s[28:29] op_sel_hi:[1,0]
	v_cvt_pk_bf16_f32 v244, v48, v49
	v_cvt_pk_bf16_f32 v245, v50, v51
	v_cvt_pk_bf16_f32 v246, v52, v53
	v_cvt_pk_bf16_f32 v247, v54, v55
	global_store_dwordx4 v169, v[244:247], s[98:99]
	s_add_u32 s26, s26, 0x800
	s_addc_u32 s27, s27, 0
	s_add_u32 s98, s98, 0x800
	s_addc_u32 s99, s99, 0
	v_pk_mul_f32 v[104:105], v[104:105], s[28:29] op_sel_hi:[1,0]
	v_pk_mul_f32 v[106:107], v[106:107], s[28:29] op_sel_hi:[1,0]
	v_pk_mul_f32 v[108:109], v[108:109], s[28:29] op_sel_hi:[1,0]
	v_pk_mul_f32 v[110:111], v[110:111], s[28:29] op_sel_hi:[1,0]
; __device__ __forceinline__ unsigned cvt_pk_bf16(float lo, float hi) { const f32x2c v = {lo, hi}; const bf16x2c b = __builtin_convertvector(v, bf16x2c); return __builtin_bit_cast(unsigned, b); }
; #define PG8_GAS __attribute__((address_space(1)))
;     __device__ __forceinline__ void operator()(const f32x4 (&acc)[2][2][4][2], const Unit& u, int wr, int wc, int fr, int fq) const {
;     ...
;                         if (seg == 0) { v0 = v0 * 0.18033688011112042f; v1 = v1 * 0.18033688011112042f; }
;                         u32x4 w; w.x = cvt_pk_bf16(v0[0], v0[1]); w.y = cvt_pk_bf16(v0[2], v0[3]); w.z = cvt_pk_bf16(v1[0], v1[1]); w.w = cvt_pk_bf16(v1[2], v1[3]);
;                         *(PG8_GAS u32x4*)(segp + ((size_t)((b * 8 + head) * 8192 + s)) * 64 + ch) = w;
	v_cvt_pk_bf16_f32 v248, v104, v105
	v_cvt_pk_bf16_f32 v249, v106, v107
	v_cvt_pk_bf16_f32 v250, v108, v109
	v_cvt_pk_bf16_f32 v251, v110, v111
	global_store_dwordx4 v169, v[248:251], s[26:27]
	v_pk_mul_f32 v[40:41], v[40:41], s[28:29] op_sel_hi:[1,0]
	v_pk_mul_f32 v[42:43], v[42:43], s[28:29] op_sel_hi:[1,0]
	v_pk_mul_f32 v[44:45], v[44:45], s[28:29] op_sel_hi:[1,0]
	v_pk_mul_f32 v[46:47], v[46:47], s[28:29] op_sel_hi:[1,0]
	v_cvt_pk_bf16_f32 v244, v40, v41
	v_cvt_pk_bf16_f32 v245, v42, v43
	v_cvt_pk_bf16_f32 v246, v44, v45
	v_cvt_pk_bf16_f32 v247, v46, v47
	global_store_dwordx4 v169, v[244:247], s[98:99]
	s_add_u32 s26, s26, 0x800
	s_addc_u32 s27, s27, 0
	s_add_u32 s98, s98, 0x800
	s_addc_u32 s99, s99, 0
	v_pk_mul_f32 v[96:97], v[96:97], s[28:29] op_sel_hi:[1,0]
	v_pk_mul_f32 v[98:99], v[98:99], s[28:29] op_sel_hi:[1,0]
	v_pk_mul_f32 v[100:101], v[100:101], s[28:29] op_sel_hi:[1,0]
	v_pk_mul_f32 v[102:103], v[102:103], s[28:29] op_sel_hi:[1,0]
	v_cvt_pk_bf16_f32 v248, v96, v97
	v_cvt_pk_bf16_f32 v249, v98, v99
	v_cvt_pk_bf16_f32 v250, v100, v101
	v_cvt_pk_bf16_f32 v251, v102, v103
	global_store_dwordx4 v169, v[248:251], s[26:27]
	v_pk_mul_f32 v[32:33], v[32:33], s[28:29] op_sel_hi:[1,0]
	v_pk_mul_f32 v[34:35], v[34:35], s[28:29] op_sel_hi:[1,0]
	v_pk_mul_f32 v[36:37], v[36:37], s[28:29] op_sel_hi:[1,0]
	v_pk_mul_f32 v[38:39], v[38:39], s[28:29] op_sel_hi:[1,0]
	v_cvt_pk_bf16_f32 v244, v32, v33
	v_cvt_pk_bf16_f32 v245, v34, v35
	v_cvt_pk_bf16_f32 v246, v36, v37
	v_cvt_pk_bf16_f32 v247, v38, v39
	global_store_dwordx4 v169, v[244:247], s[98:99]
	s_add_u32 s26, s26, 0x2800
	s_addc_u32 s27, s27, 0
	s_add_u32 s98, s98, 0x2800
	s_addc_u32 s99, s99, 0
	v_pk_mul_f32 v[88:89], v[88:89], s[28:29] op_sel_hi:[1,0]
	v_pk_mul_f32 v[90:91], v[90:91], s[28:29] op_sel_hi:[1,0]
	v_pk_mul_f32 v[92:93], v[92:93], s[28:29] op_sel_hi:[1,0]
	v_pk_mul_f32 v[94:95], v[94:95], s[28:29] op_sel_hi:[1,0]
	v_cvt_pk_bf16_f32 v248, v88, v89
	v_cvt_pk_bf16_f32 v249, v90, v91
	v_cvt_pk_bf16_f32 v250, v92, v93
	v_cvt_pk_bf16_f32 v251, v94, v95
	global_store_dwordx4 v169, v[248:251], s[26:27]
	v_pk_mul_f32 v[24:25], v[24:25], s[28:29] op_sel_hi:[1,0]
	v_pk_mul_f32 v[26:27], v[26:27], s[28:29] op_sel_hi:[1,0]
	v_pk_mul_f32 v[28:29], v[28:29], s[28:29] op_sel_hi:[1,0]
	v_pk_mul_f32 v[30:31], v[30:31], s[28:29] op_sel_hi:[1,0]
	v_cvt_pk_bf16_f32 v244, v24, v25
	v_cvt_pk_bf16_f32 v245, v26, v27
	v_cvt_pk_bf16_f32 v246, v28, v29
	v_cvt_pk_bf16_f32 v247, v30, v31
	global_store_dwordx4 v169, v[244:247], s[98:99]
	s_add_u32 s26, s26, 0x800
	s_addc_u32 s27, s27, 0
	s_add_u32 s98, s98, 0x800
	s_addc_u32 s99, s99, 0
	v_pk_mul_f32 v[80:81], v[80:81], s[28:29] op_sel_hi:[1,0]
	v_pk_mul_f32 v[82:83], v[82:83], s[28:29] op_sel_hi:[1,0]
	v_pk_mul_f32 v[84:85], v[84:85], s[28:29] op_sel_hi:[1,0]
	v_pk_mul_f32 v[86:87], v[86:87], s[28:29] op_sel_hi:[1,0]
	v_cvt_pk_bf16_f32 v248, v80, v81
	v_cvt_pk_bf16_f32 v249, v82, v83
	v_cvt_pk_bf16_f32 v250, v84, v85
	v_cvt_pk_bf16_f32 v251, v86, v87
	global_store_dwordx4 v169, v[248:251], s[26:27]
	v_pk_mul_f32 v[16:17], v[16:17], s[28:29] op_sel_hi:[1,0]
	v_pk_mul_f32 v[18:19], v[18:19], s[28:29] op_sel_hi:[1,0]
	v_pk_mul_f32 v[20:21], v[20:21], s[28:29] op_sel_hi:[1,0]
	v_pk_mul_f32 v[22:23], v[22:23], s[28:29] op_sel_hi:[1,0]
	v_cvt_pk_bf16_f32 v244, v16, v17
	v_cvt_pk_bf16_f32 v245, v18, v19
	v_cvt_pk_bf16_f32 v246, v20, v21
	v_cvt_pk_bf16_f32 v247, v22, v23
	global_store_dwordx4 v169, v[244:247], s[98:99]
	s_add_u32 s26, s26, 0x800
	s_addc_u32 s27, s27, 0
	s_add_u32 s98, s98, 0x800
	s_addc_u32 s99, s99, 0
	v_pk_mul_f32 v[72:73], v[72:73], s[28:29] op_sel_hi:[1,0]
	v_pk_mul_f32 v[74:75], v[74:75], s[28:29] op_sel_hi:[1,0]
	v_pk_mul_f32 v[76:77], v[76:77], s[28:29] op_sel_hi:[1,0]
	v_pk_mul_f32 v[78:79], v[78:79], s[28:29] op_sel_hi:[1,0]
	v_cvt_pk_bf16_f32 v248, v72, v73
	v_cvt_pk_bf16_f32 v249, v74, v75
	v_cvt_pk_bf16_f32 v250, v76, v77
	v_cvt_pk_bf16_f32 v251, v78, v79
	global_store_dwordx4 v169, v[248:251], s[26:27]
	v_pk_mul_f32 v[8:9], v[8:9], s[28:29] op_sel_hi:[1,0]
	v_pk_mul_f32 v[10:11], v[10:11], s[28:29] op_sel_hi:[1,0]
	v_pk_mul_f32 v[12:13], v[12:13], s[28:29] op_sel_hi:[1,0]
	v_pk_mul_f32 v[14:15], v[14:15], s[28:29] op_sel_hi:[1,0]
	v_cvt_pk_bf16_f32 v244, v8, v9
	v_cvt_pk_bf16_f32 v245, v10, v11
	v_cvt_pk_bf16_f32 v246, v12, v13
	v_cvt_pk_bf16_f32 v247, v14, v15
	global_store_dwordx4 v169, v[244:247], s[98:99]
	s_add_u32 s26, s26, 0x800
	s_addc_u32 s27, s27, 0
	s_add_u32 s98, s98, 0x800
	s_addc_u32 s99, s99, 0
	v_pk_mul_f32 v[64:65], v[64:65], s[28:29] op_sel_hi:[1,0]
	v_pk_mul_f32 v[66:67], v[66:67], s[28:29] op_sel_hi:[1,0]
	v_pk_mul_f32 v[68:69], v[68:69], s[28:29] op_sel_hi:[1,0]
	v_pk_mul_f32 v[70:71], v[70:71], s[28:29] op_sel_hi:[1,0]
	v_cvt_pk_bf16_f32 v248, v64, v65
	v_cvt_pk_bf16_f32 v249, v66, v67
	v_cvt_pk_bf16_f32 v250, v68, v69
	v_cvt_pk_bf16_f32 v251, v70, v71
	global_store_dwordx4 v169, v[248:251], s[26:27]
	v_pk_mul_f32 v[4:5], v[4:5], s[28:29] op_sel_hi:[1,0]
	v_pk_mul_f32 v[6:7], v[6:7], s[28:29] op_sel_hi:[1,0]
	v_pk_mul_f32 v[0:1], v[0:1], s[28:29] op_sel_hi:[1,0]
	v_pk_mul_f32 v[2:3], v[2:3], s[28:29] op_sel_hi:[1,0]
	v_cvt_pk_bf16_f32 v244, v4, v5
	v_cvt_pk_bf16_f32 v245, v6, v7
	v_cvt_pk_bf16_f32 v246, v0, v1
	v_cvt_pk_bf16_f32 v247, v2, v3
	global_store_dwordx4 v169, v[244:247], s[98:99]
.Lrope_done:
	s_andn2_b64 vcc, exec, s[8:9]
	s_mov_b64 s[0:1], -1
	s_cbranch_vccnz .LBB0_146
	s_branch .Lmix_hasnext

; #define PG8_BAR __builtin_amdgcn_s_barrier()
; template <class Epi, class Sched, bool ALIGN_EPI = false, bool SP2 = false>
; __device__ __forceinline__ void gemm_phase(PG8_LAS unsigned char* lds, const Gemm g, const Sched& S, const Epi& E, const int tid) {
;     ...
;         if (!has_next) break;
; #pragma unroll
;         for (int a = 0; a < 2; ++a)
; #pragma unroll
;             for (int b = 0; b < 2; ++b)
; #pragma unroll
;                 for (int m = 0; m < 4; ++m)
; #pragma unroll
;                     for (int n = 0; n < 2; ++n) acc[a][b][m][n] = (f32x4){0.f, 0.f, 0.f, 0.f};
;         cur = nxt; cA = nA; cB = nB; ++ui;
;         if constexpr (ALIGN_EPI) { if (wr == 1) PG8_BAR; }
;     }
.Lmix_hasnext:
	v_readlane_b32 s0, v255, 10
	v_readlane_b32 s1, v255, 11
	s_andn2_b64 vcc, exec, s[0:1]
	s_cbranch_vccnz .LBB0_145
	s_barrier
	s_branch .LBB0_145
